# comb3 + softmax-chain trimming bundle: E1 (max tree, 4 partial sums), K1 (3-deep QK read pipeline), nop-free DMA issue order, unmasked alpha write, dead scalar ops removed
# baseline (speedup 1.0000x reference)
; #define SBAR() __builtin_amdgcn_sched_barrier(0)
; #define A2_LOADT(t) do { const size_t ro_ = (size_t)((t) * 64 + sr) * D + sc; \
;         sk0 = att::load8(c.K + ro_); sk1 = att::load8(c.K + ro_ + 32 * D); sv00 = att::load8(c.V0 + ro_); sv01 = att::load8(c.V0 + ro_ + 32 * D); sv10 = att::load8(c.V1 + ro_); sv11 = att::load8(c.V1 + ro_ + 32 * D); } while (0)
; __device__ __forceinline__ void qkt_rt(f32x16& p0, f32x16& p1, const char* Kb, int r32, int hi, const bf16x8* qr) {
;     p0 = f32x16{}; p1 = f32x16{};
;     const char* kb[4];
; #pragma unroll
;     for (int dd = 0; dd < 4; ++dd) kb[dd] = Kb + KSWZ(r32, (dd * 16 + hi * 8) * 2);
; #pragma unroll
;     for (int d0 = 0; d0 < 8; ++d0) { const char* a = kb[d0 & 3] + (d0 >> 2) * 128;
;         bf16x8 b0 = *reinterpret_cast<const bf16x8*>(a);
;         bf16x8 b1 = *reinterpret_cast<const bf16x8*>(a + 32 * 256);
;         p0 = __builtin_amdgcn_mfma_f32_32x32x16_bf16(b0, qr[d0], p0, 0, 0, 0);
;         p1 = __builtin_amdgcn_mfma_f32_32x32x16_bf16(b1, qr[d0], p1, 0, 0, 0); }
; __device__ __forceinline__ void attn2_block(const Blk& c, char* lds) {
;     ...
;             if (s + 1 < NT) A2_LOADT(s + 1);
;             SBAR();
;             if (s < NT) {
;                 f32x16 p0, p1; float mn, al; bf16x8 pa0, pa1, pa2, pa3;
;                 qkt_rt(p0, p1, lds + L_K + par * SHM_K, r32, hi, qr);
;                 const int kb_ = s * 64;
;                 if (kb_ + 63 > qlo - 128) att::bias_mask_tile(p0, p1, qm - kb_, bt);
.LBB0_552:
	s_and_b32 s88, s30, 1
	s_lshl_b32 s10, s88, 15
	s_add_i32 s10, s10, s100
	s_xor_b32 s11, s88, 1
	s_lshl_b32 s11, s11, 14
	s_add_i32 s11, s11, s100
	s_mov_b32 m0, s10
	v_lshl_add_u64 v[52:53], v[168:169], 0, s[82:83]
	global_load_lds_dwordx4 v[52:53], off
	s_add_i32 m0, s10, 0x380
	v_lshl_add_u64 v[54:55], v[170:171], 0, s[82:83]
	global_load_lds_dwordx4 v[52:53], off offset:128
	s_add_i32 m0, s10, 0x4000
	v_lshl_add_u64 v[56:57], v[164:165], 0, s[82:83]
	global_load_lds_dwordx4 v[54:55], off
	s_add_i32 m0, s10, 0x4380
	v_lshl_add_u64 v[58:59], v[166:167], 0, s[82:83]
	global_load_lds_dwordx4 v[54:55], off offset:128
	s_add_i32 m0, s11, 0x10000
	s_lshl_b32 s10, s88, 14
	global_load_lds_dwordx4 v[56:57], off
	global_load_lds_dwordx4 v[58:59], off offset:1024
	s_add_i32 s10, s10, 0x10000
	v_add3_u32 v40, s10, v121, v119
	ds_read_b128 v[36:39], v40
	ds_read_b128 v[48:51], v40 offset:8192
	v_add3_u32 v41, s10, v122, v119
	ds_read_b128 v[60:63], v41
	v_add3_u32 v42, s10, v123, v119
	v_add3_u32 v43, s10, v124, v119
	v_add3_u32 v44, s10, v126, v119
	v_add3_u32 v45, s10, v127, v119
	v_add3_u32 v46, s10, v128, v119
	v_add3_u32 v47, s10, v129, v119
	s_add_i32 s10, s84, 63
	s_cmp_le_i32 s10, s86
	s_waitcnt lgkmcnt(2)
	v_mfma_f32_32x32x16_bf16 v[20:35], v[36:39], v[104:107], 0
	ds_read_b128 v[64:67], v41 offset:8192
	s_waitcnt lgkmcnt(2)
	v_mfma_f32_32x32x16_bf16 v[4:19], v[48:51], v[104:107], 0
	ds_read_b128 v[36:39], v42
	s_waitcnt lgkmcnt(2)
	v_mfma_f32_32x32x16_bf16 v[20:35], v[60:63], v[100:103], v[20:35]
	ds_read_b128 v[48:51], v42 offset:8192
	s_waitcnt lgkmcnt(2)
	v_mfma_f32_32x32x16_bf16 v[4:19], v[64:67], v[100:103], v[4:19]
	ds_read_b128 v[60:63], v43
	s_waitcnt lgkmcnt(2)
	v_mfma_f32_32x32x16_bf16 v[20:35], v[36:39], v[96:99], v[20:35]
	ds_read_b128 v[64:67], v43 offset:8192
	s_waitcnt lgkmcnt(2)
	v_mfma_f32_32x32x16_bf16 v[4:19], v[48:51], v[96:99], v[4:19]
	ds_read_b128 v[36:39], v44
	s_waitcnt lgkmcnt(2)
	v_mfma_f32_32x32x16_bf16 v[20:35], v[60:63], v[92:95], v[20:35]
	ds_read_b128 v[48:51], v44 offset:8192
	s_waitcnt lgkmcnt(2)
	v_mfma_f32_32x32x16_bf16 v[4:19], v[64:67], v[92:95], v[4:19]
	ds_read_b128 v[60:63], v45
	s_waitcnt lgkmcnt(2)
	v_mfma_f32_32x32x16_bf16 v[20:35], v[36:39], v[88:91], v[20:35]
	ds_read_b128 v[64:67], v45 offset:8192
	s_waitcnt lgkmcnt(2)
	v_mfma_f32_32x32x16_bf16 v[4:19], v[48:51], v[88:91], v[4:19]
	ds_read_b128 v[36:39], v46
	s_waitcnt lgkmcnt(2)
	v_mfma_f32_32x32x16_bf16 v[20:35], v[60:63], v[84:87], v[20:35]
	ds_read_b128 v[48:51], v46 offset:8192
	s_waitcnt lgkmcnt(2)
	v_mfma_f32_32x32x16_bf16 v[4:19], v[64:67], v[84:87], v[4:19]
	ds_read_b128 v[60:63], v47
	s_waitcnt lgkmcnt(2)
	v_mfma_f32_32x32x16_bf16 v[20:35], v[36:39], v[80:83], v[20:35]
	ds_read_b128 v[64:67], v47 offset:8192
	s_waitcnt lgkmcnt(2)
	v_mfma_f32_32x32x16_bf16 v[4:19], v[48:51], v[80:83], v[4:19]
	s_waitcnt lgkmcnt(1)
	v_mfma_f32_32x32x16_bf16 v[20:35], v[60:63], v[76:79], v[20:35]
	s_waitcnt lgkmcnt(0)
	v_mfma_f32_32x32x16_bf16 v[4:19], v[64:67], v[76:79], v[4:19]
	s_cbranch_scc1 .LBB0_586
	v_add_u32_e32 v115, 27, v125
	v_lshl_add_u32 v36, v115, 2, s64
	v_add_u32_e32 v36, 0xffffff14, v36
	ds_read_b32 v132, v36 offset:236
	ds_read_b32 v133, v36 offset:232
	ds_read_b32 v134, v36 offset:228
	ds_read_b32 v135, v36 offset:224
	ds_read_b32 v136, v36 offset:204
	ds_read_b32 v137, v36 offset:200
	ds_read_b32 v138, v36 offset:196
	ds_read_b32 v139, v36 offset:192
	ds_read_b32 v140, v36 offset:172
	ds_read_b32 v141, v36 offset:168
	ds_read_b32 v142, v36 offset:164
	ds_read_b32 v143, v36 offset:160
	ds_read_b32 v144, v36 offset:140
	ds_read_b32 v145, v36 offset:136
	ds_read_b32 v146, v36 offset:132
	v_cmp_lt_i32_e32 vcc, -1, v115
	v_cmp_lt_i32_e64 s[16:17], 0, v115
	s_waitcnt lgkmcnt(14)
	v_add_f32_e32 v20, v20, v132
	ds_read_b32 v147, v36 offset:128
	s_waitcnt lgkmcnt(14)
	v_add_f32_e32 v21, v21, v133
	ds_read_b32 v148, v36 offset:108
	v_cndmask_b32_e32 v20, v240, v20, vcc
	v_cndmask_b32_e64 v21, v240, v21, s[16:17]
	v_cmp_lt_i32_e32 vcc, 1, v115
	v_cmp_lt_i32_e64 s[16:17], 2, v115
	s_waitcnt lgkmcnt(14)
	v_add_f32_e32 v22, v22, v134
	ds_read_b32 v149, v36 offset:104
	s_waitcnt lgkmcnt(14)
	v_add_f32_e32 v23, v23, v135
	ds_read_b32 v150, v36 offset:100
	v_cndmask_b32_e32 v22, v240, v22, vcc
	v_cndmask_b32_e64 v23, v240, v23, s[16:17]
	v_cmp_lt_i32_e32 vcc, 7, v115
	v_cmp_lt_i32_e64 s[16:17], 8, v115
	s_waitcnt lgkmcnt(14)
	v_add_f32_e32 v24, v24, v136
	ds_read_b32 v151, v36 offset:96
	s_waitcnt lgkmcnt(14)
	v_add_f32_e32 v25, v25, v137
	ds_read_b32 v152, v36 offset:76
	v_cndmask_b32_e32 v24, v240, v24, vcc
	v_cndmask_b32_e64 v25, v240, v25, s[16:17]
	v_cmp_lt_i32_e32 vcc, 9, v115
	v_cmp_lt_i32_e64 s[16:17], 10, v115
	s_waitcnt lgkmcnt(14)
	v_add_f32_e32 v26, v26, v138
	ds_read_b32 v153, v36 offset:72
	s_waitcnt lgkmcnt(14)
	v_add_f32_e32 v27, v27, v139
	ds_read_b32 v154, v36 offset:68
	v_cndmask_b32_e32 v26, v240, v26, vcc
	v_cndmask_b32_e64 v27, v240, v27, s[16:17]
	v_cmp_lt_i32_e32 vcc, 15, v115
	v_cmp_lt_i32_e64 s[16:17], 16, v115
	s_waitcnt lgkmcnt(14)
	v_add_f32_e32 v28, v28, v140
	ds_read_b32 v155, v36 offset:64
	s_waitcnt lgkmcnt(14)
	v_add_f32_e32 v29, v29, v141
	ds_read_b32 v60, v36 offset:44
	v_cndmask_b32_e32 v28, v240, v28, vcc
	v_cndmask_b32_e64 v29, v240, v29, s[16:17]
	v_cmp_lt_i32_e32 vcc, 17, v115
	v_cmp_lt_i32_e64 s[16:17], 18, v115
	s_waitcnt lgkmcnt(14)
	v_add_f32_e32 v30, v30, v142
	ds_read_b32 v61, v36 offset:40
	s_waitcnt lgkmcnt(14)
	v_add_f32_e32 v31, v31, v143
	ds_read_b32 v62, v36 offset:36
	v_cndmask_b32_e32 v30, v240, v30, vcc
	v_cndmask_b32_e64 v31, v240, v31, s[16:17]
	v_cmp_lt_i32_e32 vcc, 23, v115
	v_cmp_lt_i32_e64 s[16:17], 24, v115
	s_waitcnt lgkmcnt(14)
; __device__ __forceinline__ void bias_mask_tile(f32x16& p0, f32x16& p1, int dq, const float* bt) {
;     const float NEG = -__builtin_inff();
; #pragma unroll
;     for (int r = 0; r < 16; ++r) {
;         const int c = (r & 3) + 8 * (r >> 2);
;         const int d0 = dq - c, d1 = dq - c - 32;
;         const unsigned i0 = (unsigned)d0 < 255u ? (unsigned)d0 : 255u, i1 = (unsigned)d1 < 255u ? (unsigned)d1 : 255u;
;         const float b0 = bt[i0], b1 = bt[i1];
;         p0[r] = d0 >= 0 ? p0[r] + b0 : NEG;
;         p1[r] = d1 >= 0 ? p1[r] + b1 : NEG;
;     }
; }
	v_add_f32_e32 v32, v32, v144
	ds_read_b32 v63, v36 offset:32
	s_waitcnt lgkmcnt(14)
	v_add_f32_e32 v33, v33, v145
	ds_read_b32 v64, v36 offset:12
	v_cndmask_b32_e32 v32, v240, v32, vcc
	v_cndmask_b32_e64 v33, v240, v33, s[16:17]
	v_cmp_lt_i32_e32 vcc, 25, v115
	v_cmp_lt_i32_e64 s[16:17], 26, v115
	s_waitcnt lgkmcnt(14)
	v_add_f32_e32 v34, v34, v146
	ds_read_b32 v65, v36 offset:8
	s_waitcnt lgkmcnt(14)
	v_add_f32_e32 v35, v35, v147
	ds_read_b32 v66, v36 offset:4
	v_cndmask_b32_e32 v34, v240, v34, vcc
	v_cndmask_b32_e64 v35, v240, v35, s[16:17]
	v_cmp_lt_i32_e32 vcc, 31, v115
	v_cmp_lt_i32_e64 s[16:17], 32, v115
	s_waitcnt lgkmcnt(14)
	v_add_f32_e32 v4, v4, v148
	ds_read_b32 v67, v36 offset:0
	s_waitcnt lgkmcnt(14)
	v_add_f32_e32 v5, v5, v149
	v_cndmask_b32_e32 v4, v240, v4, vcc
	v_cndmask_b32_e64 v5, v240, v5, s[16:17]
	v_cmp_lt_i32_e32 vcc, 33, v115
	v_cmp_lt_i32_e64 s[16:17], 34, v115
	s_waitcnt lgkmcnt(13)
	v_add_f32_e32 v6, v6, v150
	s_waitcnt lgkmcnt(12)
	v_add_f32_e32 v7, v7, v151
	v_cndmask_b32_e32 v6, v240, v6, vcc
	v_cndmask_b32_e64 v7, v240, v7, s[16:17]
	v_cmp_lt_i32_e32 vcc, 39, v115
	v_cmp_lt_i32_e64 s[16:17], 40, v115
	s_waitcnt lgkmcnt(11)
	v_add_f32_e32 v8, v8, v152
	s_waitcnt lgkmcnt(10)
	v_add_f32_e32 v9, v9, v153
	v_cndmask_b32_e32 v8, v240, v8, vcc
	v_cndmask_b32_e64 v9, v240, v9, s[16:17]
	v_cmp_lt_i32_e32 vcc, 41, v115
	v_cmp_lt_i32_e64 s[16:17], 42, v115
	s_waitcnt lgkmcnt(9)
	v_add_f32_e32 v10, v10, v154
	s_waitcnt lgkmcnt(8)
	v_add_f32_e32 v11, v11, v155
	v_cndmask_b32_e32 v10, v240, v10, vcc
	v_cndmask_b32_e64 v11, v240, v11, s[16:17]
	v_cmp_lt_i32_e32 vcc, 47, v115
	v_cmp_lt_i32_e64 s[16:17], 48, v115
	s_waitcnt lgkmcnt(7)
	v_add_f32_e32 v12, v12, v60
	s_waitcnt lgkmcnt(6)
	v_add_f32_e32 v13, v13, v61
	v_cndmask_b32_e32 v12, v240, v12, vcc
	v_cndmask_b32_e64 v13, v240, v13, s[16:17]
	v_cmp_lt_i32_e32 vcc, 49, v115
	v_cmp_lt_i32_e64 s[16:17], 50, v115
	s_waitcnt lgkmcnt(5)
	v_add_f32_e32 v14, v14, v62
	s_waitcnt lgkmcnt(4)
	v_add_f32_e32 v15, v15, v63
	v_cndmask_b32_e32 v14, v240, v14, vcc
	v_cndmask_b32_e64 v15, v240, v15, s[16:17]
	v_cmp_lt_i32_e32 vcc, 55, v115
	v_cmp_lt_i32_e64 s[16:17], 56, v115
	s_waitcnt lgkmcnt(3)
	v_add_f32_e32 v16, v16, v64
	s_waitcnt lgkmcnt(2)
	v_add_f32_e32 v17, v17, v65
	v_cndmask_b32_e32 v16, v240, v16, vcc
	v_cndmask_b32_e64 v17, v240, v17, s[16:17]
	v_cmp_lt_i32_e32 vcc, 57, v115
	v_cmp_lt_i32_e64 s[16:17], 58, v115
	s_waitcnt lgkmcnt(1)
	v_add_f32_e32 v18, v18, v66
	s_waitcnt lgkmcnt(0)
	v_add_f32_e32 v19, v19, v67
	v_cndmask_b32_e32 v18, v240, v18, vcc
	v_cndmask_b32_e64 v19, v240, v19, s[16:17]
; __device__ __forceinline__ void partialSM(f32x16& p0, f32x16& p1, float& m_reg, float& mn, float& alpha) {
;     float pmax = p0[0]; for (int r = 1; r < 16; ++r) pmax = fmaxf(pmax, p0[r]); for (int r = 0; r < 16; ++r) pmax = fmaxf(pmax, p1[r]);
;     { auto rr = __builtin_amdgcn_permlane32_swap(__float_as_uint(pmax), __float_as_uint(pmax), false, false);
;       pmax = fmaxf(__uint_as_float(rr[0]), __uint_as_float(rr[1])); }
;     constexpr float C2 = 1.4426950408889634f * SCALE;
;     if (__builtin_expect(__all((pmax - m_reg) * SCALE <= THR), 1)) { mn = m_reg; alpha = 1.f; }
;     else { mn = fmaxf(m_reg, pmax); alpha = __builtin_amdgcn_exp2f((m_reg - mn) * C2); m_reg = mn; }
;     const float mnL = -mn * C2;
;     for (int r = 0; r < 16; ++r) p0[r] = fmaf(p0[r], C2, mnL); for (int r = 0; r < 16; ++r) p1[r] = fmaf(p1[r], C2, mnL);
;     for (int r = 0; r < 16; ++r) p0[r] = __builtin_amdgcn_exp2f(p0[r]);
; }
; __device__ __forceinline__ void finishSM(f32x16& p0, f32x16& p1, float alpha, float& l_reg, bf16x8& pa0, bf16x8& pa1, bf16x8& pa2, bf16x8& pa3) {
;     for (int r = 0; r < 16; ++r) p1[r] = __builtin_amdgcn_exp2f(p1[r]);
;     float ps = 0; for (int r = 0; r < 16; ++r) ps += p0[r]; for (int r = 0; r < 16; ++r) ps += p1[r];
;     { auto rr = __builtin_amdgcn_permlane32_swap(__float_as_uint(ps), __float_as_uint(ps), false, false);
;       ps = __uint_as_float(rr[0]) + __uint_as_float(rr[1]); }
;     l_reg = l_reg * alpha + ps;
;     ...
;     PK4(p0, 0, pa0); PK4(p0, 8, pa1); PK4(p1, 0, pa2); PK4(p1, 8, pa3);
; __device__ __forceinline__ void attn2_block(const Blk& c, char* lds) {
;     ...
;                 att::partialSM(p0, p1, m_reg, mn, al);
;                 att::finishSM(p0, p1, al, l_reg, pa0, pa1, pa2, pa3);
;                 char* pw = Pb + par * 4096 + lane * 16;
;                 *(bf16x8*)(pw) = pa0; *(bf16x8*)(pw + 1024) = pa1; *(bf16x8*)(pw + 2048) = pa2; *(bf16x8*)(pw + 3072) = pa3;
;                 if (hi == 0) ALb[par * 32 + r32] = al;
;                 const bool resc = __any(al < 1.f);
;                 if (lane == 0) FLb[par] = resc ? 1u : 0u;
.LBB0_586:
	s_nop 7
	v_max3_f32 v36, v20, v21, v22
	v_max3_f32 v38, v23, v24, v25
	v_max3_f32 v39, v26, v27, v28
	v_max3_f32 v40, v29, v30, v31
	v_max3_f32 v41, v32, v33, v34
	v_max3_f32 v42, v4, v5, v6
	v_max3_f32 v43, v7, v8, v9
	v_max3_f32 v44, v10, v11, v12
	v_max3_f32 v45, v13, v14, v15
	v_max3_f32 v46, v16, v17, v18
	v_max3_f32 v36, v36, v38, v39
	v_max3_f32 v40, v40, v41, v35
	v_max3_f32 v42, v42, v43, v44
	v_max3_f32 v45, v45, v46, v19
	v_max3_f32 v36, v36, v40, v42
	v_max_f32_e32 v36, v36, v45
	v_mov_b32_e32 v37, v36
	s_nop 1
	v_permlane32_swap_b32_e32 v36, v37
	v_max_f32_e32 v36, v36, v37
	v_sub_f32_e32 v37, v36, v113
	v_mul_f32_e32 v37, 0x3db504f3, v37
	v_cmp_ge_f32_e32 vcc, s48, v37
	v_max_f32_e32 v38, v113, v36
	s_cmp_eq_u64 vcc, exec
	s_cselect_b64 vcc, -1, 0
	v_sub_f32_e32 v36, v113, v38
	v_cndmask_b32_e32 v113, v38, v113, vcc
	v_mul_f32_e32 v37, 0xbe0293ee, v113
	v_fmamk_f32 v20, v20, 0x3e0293ee, v37
	v_fmamk_f32 v21, v21, 0x3e0293ee, v37
	v_fmamk_f32 v22, v22, 0x3e0293ee, v37
	v_fmamk_f32 v23, v23, 0x3e0293ee, v37
	v_fmamk_f32 v24, v24, 0x3e0293ee, v37
	v_fmamk_f32 v25, v25, 0x3e0293ee, v37
	v_fmamk_f32 v26, v26, 0x3e0293ee, v37
	v_fmamk_f32 v27, v27, 0x3e0293ee, v37
	v_fmamk_f32 v28, v28, 0x3e0293ee, v37
	v_fmamk_f32 v29, v29, 0x3e0293ee, v37
	v_fmamk_f32 v30, v30, 0x3e0293ee, v37
	v_fmamk_f32 v31, v31, 0x3e0293ee, v37
	v_fmamk_f32 v32, v32, 0x3e0293ee, v37
	v_fmamk_f32 v33, v33, 0x3e0293ee, v37
	v_fmamk_f32 v34, v34, 0x3e0293ee, v37
	v_fmamk_f32 v35, v35, 0x3e0293ee, v37
	v_fmamk_f32 v4, v4, 0x3e0293ee, v37
	v_fmamk_f32 v5, v5, 0x3e0293ee, v37
	v_fmamk_f32 v6, v6, 0x3e0293ee, v37
	v_fmamk_f32 v7, v7, 0x3e0293ee, v37
	v_fmamk_f32 v8, v8, 0x3e0293ee, v37
	v_fmamk_f32 v9, v9, 0x3e0293ee, v37
	v_fmamk_f32 v10, v10, 0x3e0293ee, v37
	v_fmamk_f32 v11, v11, 0x3e0293ee, v37
	v_fmamk_f32 v12, v12, 0x3e0293ee, v37
	v_fmamk_f32 v13, v13, 0x3e0293ee, v37
	v_fmamk_f32 v14, v14, 0x3e0293ee, v37
	v_fmamk_f32 v15, v15, 0x3e0293ee, v37
	v_fmamk_f32 v16, v16, 0x3e0293ee, v37
	v_fmamk_f32 v17, v17, 0x3e0293ee, v37
	v_fmamk_f32 v18, v18, 0x3e0293ee, v37
	v_fmac_f32_e32 v37, 0x3e0293ee, v19
	v_exp_f32_e32 v19, v20
	v_exp_f32_e32 v20, v21
	v_exp_f32_e32 v21, v22
	v_exp_f32_e32 v22, v23
	v_exp_f32_e32 v23, v24
	v_exp_f32_e32 v24, v25
	v_add_f32_e32 v60, v19, v23
	v_exp_f32_e32 v25, v26
	v_add_f32_e32 v61, v20, v24
	v_exp_f32_e32 v26, v27
	v_add_f32_e32 v62, v21, v25
	v_exp_f32_e32 v27, v28
	v_add_f32_e32 v63, v22, v26
	v_exp_f32_e32 v28, v29
	v_add_f32_e32 v60, v27, v60
	v_exp_f32_e32 v29, v30
	v_add_f32_e32 v61, v28, v61
	v_exp_f32_e32 v30, v31
	v_add_f32_e32 v62, v29, v62
	v_exp_f32_e32 v31, v32
	v_add_f32_e32 v63, v30, v63
	v_exp_f32_e32 v32, v33
	v_add_f32_e32 v60, v31, v60
	v_exp_f32_e32 v33, v34
	v_add_f32_e32 v61, v32, v61
	v_exp_f32_e32 v34, v35
	v_add_f32_e32 v62, v33, v62
	v_exp_f32_e32 v35, v4
	v_add_f32_e32 v63, v34, v63
	v_exp_f32_e32 v38, v5
	v_add_f32_e32 v60, v35, v60
	v_exp_f32_e32 v39, v6
	v_add_f32_e32 v61, v38, v61
	v_exp_f32_e32 v40, v7
	v_add_f32_e32 v62, v39, v62
	v_exp_f32_e32 v41, v8
	v_add_f32_e32 v63, v40, v63
	v_exp_f32_e32 v42, v9
	v_add_f32_e32 v60, v41, v60
	v_exp_f32_e32 v43, v10
	v_add_f32_e32 v61, v42, v61
	v_exp_f32_e32 v44, v11
	v_add_f32_e32 v62, v43, v62
	v_exp_f32_e32 v45, v12
	v_add_f32_e32 v63, v44, v63
	v_exp_f32_e32 v46, v13
	v_add_f32_e32 v60, v45, v60
	v_exp_f32_e32 v47, v14
	v_add_f32_e32 v61, v46, v61
	v_exp_f32_e32 v48, v15
	v_add_f32_e32 v62, v47, v62
	v_exp_f32_e32 v49, v16
	v_add_f32_e32 v63, v48, v63
	v_exp_f32_e32 v50, v17
	v_add_f32_e32 v60, v49, v60
	v_exp_f32_e32 v51, v18
	v_add_f32_e32 v61, v50, v61
	v_exp_f32_e32 v37, v37
	v_add_f32_e32 v62, v51, v62
	v_mul_f32_e32 v36, 0x3e0293ee, v36
	v_exp_f32_e32 v36, v36
	v_add_f32_e32 v63, v37, v63
	v_add_f32_e32 v60, v60, v61
	v_add_f32_e32 v62, v62, v63
	v_add_f32_e32 v4, v60, v62
	v_mov_b32_e32 v5, v4
	v_cvt_pk_bf16_f32 v6, v19, v20
	v_cvt_pk_bf16_f32 v7, v21, v22
	v_cvt_pk_bf16_f32 v8, v23, v24
	v_cvt_pk_bf16_f32 v9, v25, v26
	v_cndmask_b32_e64 v36, v36, 1.0, vcc
	s_nop 0
	v_permlane32_swap_b32_e32 v4, v5
	v_permlane32_swap_b32_e32 v6, v8
	v_permlane32_swap_b32_e32 v7, v9
	v_cvt_pk_bf16_f32 v10, v27, v28
	v_cvt_pk_bf16_f32 v11, v29, v30
	v_cvt_pk_bf16_f32 v12, v31, v32
	v_cvt_pk_bf16_f32 v13, v33, v34
	v_cvt_pk_bf16_f32 v14, v35, v38
	v_cvt_pk_bf16_f32 v15, v39, v40
	v_cvt_pk_bf16_f32 v16, v41, v42
	v_cvt_pk_bf16_f32 v17, v43, v44
	v_cvt_pk_bf16_f32 v18, v45, v46
	v_cvt_pk_bf16_f32 v19, v47, v48
	v_cvt_pk_bf16_f32 v20, v49, v50
	v_cvt_pk_bf16_f32 v21, v51, v37
	v_lshl_add_u32 v22, s88, 12, v112
	v_permlane32_swap_b32_e32 v10, v12
	v_permlane32_swap_b32_e32 v11, v13
	v_permlane32_swap_b32_e32 v14, v16
	v_permlane32_swap_b32_e32 v15, v17
	v_permlane32_swap_b32_e32 v18, v20
	v_permlane32_swap_b32_e32 v19, v21
	ds_write_b128 v22, v[6:9]
	ds_write_b128 v22, v[10:13] offset:1024
	ds_write_b128 v22, v[14:17] offset:2048
	ds_write_b128 v22, v[18:21] offset:3072
	v_lshl_add_u32 v6, s88, 7, v2
	ds_write_b32 v6, v36
	v_cmp_gt_f32_e32 vcc, 1.0, v36
	s_and_saveexec_b64 s[16:17], s[4:5]
	s_cbranch_execz .LBB0_590
	s_cmp_lg_u64 vcc, 0
	s_cselect_b64 s[90:91], -1, 0
	s_lshl_b32 s10, s88, 2
	s_add_i32 s10, s79, s10
	v_cndmask_b32_e64 v6, 0, 1, s[90:91]
	v_mov_b32_e32 v7, s10
	ds_write_b32 v7, v6
.LBB0_590:
	s_or_b64 exec, exec, s[16:17]
	s_add_i32 s30, s30, 1
	s_and_b32 s88, s30, 1
	s_lshl_b32 s16, s88, 14
	s_waitcnt lgkmcnt(0)
	s_waitcnt vmcnt(0)
	s_barrier
	s_add_u32 s82, s82, 0x4000
	v_add_f32_e32 v115, v4, v5
	s_addc_u32 s83, s83, 0
	s_add_i32 s84, s84, 64
	v_fmac_f32_e32 v115, v117, v36
	s_cmp_eq_u32 s87, s82
	v_subrev_u32_e32 v125, 64, v125
	s_cbranch_scc1 .LBB0_592
	v_mov_b32_e32 v117, v115
	s_branch .LBB0_552
